# grid barrier 6 replaced by a four-workgroup barrier per row block (same-XCD fast path checked at run time, memory write-back fallback)
# speedup vs baseline: 1.0151x; 1.0151x over previous
; DI unsigned xb_ld(unsigned* p)              { return __hip_atomic_load(p, __ATOMIC_RELAXED, __HIP_MEMORY_SCOPE_AGENT); }
; DI unsigned xb_add(unsigned* p, unsigned v) { return __hip_atomic_fetch_add(p, v, __ATOMIC_RELAXED, __HIP_MEMORY_SCOPE_AGENT); }
; #define XB_SPIN(cond, bar) do { unsigned _sp = 0; while (cond) { __builtin_amdgcn_s_sleep(1); \
;     if ((++_sp & 255u) == 0u) { if (xb_ld(&(bar)[XB_TMO])) break; if (_sp > XB_SPIN_CAP) { atomicAdd(&(bar)[XB_TMO], 1u); break; } } } } while (0)
; DI void xcd_barrier(const XcdBarrier& b) {
;     asm volatile("s_waitcnt vmcnt(0)" ::: "memory");
;     __syncthreads();
;     if (threadIdx.x == 0) {
;         unsigned* bar = b.bar;
;         __builtin_amdgcn_s_waitcnt(0);
;         unsigned nloc = b.st[0], nx = b.st[1];
;         if (nloc == 0u) { xcd_barrier_complete(bar, b.x, nloc, nx); b.st[0] = nloc; b.st[1] = nx; }
;         const unsigned old = xb_add(&bar[XB_XSUB(b.x)], 1u);
;         const unsigned gen = old / nloc;
;         if (old + 1u == (gen + 1u) * nloc) {
;             __builtin_amdgcn_fence(__ATOMIC_RELEASE, "agent");
;             asm volatile("s_waitcnt vmcnt(0)" ::: "memory");
;             const unsigned og = xb_add(&bar[XB_TOP], 1u);
;             const unsigned tg = og / nx;
;             if (og + 1u == (tg + 1u) * nx) xb_add(&bar[XB_TOPGEN], 1u);
;             else XB_SPIN(xb_ld(&bar[XB_TOPGEN]) == tg, bar);
;             __builtin_amdgcn_fence(__ATOMIC_ACQUIRE, "agent");
;             xb_add(&bar[XB_XGEN(b.x)], 1u);
;             asm volatile("s_waitcnt vmcnt(0)" ::: "memory");
;         } else {
;             XB_SPIN(xb_ld(&bar[XB_XGEN(b.x)]) == gen, bar);
;             __builtin_amdgcn_fence(__ATOMIC_ACQUIRE, "agent");
;             asm volatile("s_waitcnt vmcnt(0)" ::: "memory");
;         }
;     }
;     __syncthreads();
.LBB0_1307:
	s_waitcnt vmcnt(0) lgkmcnt(0)
	s_barrier
	v_cmp_eq_u32_e32 vcc, 0, v203
	s_and_saveexec_b64 s[6:7], vcc
	s_cbranch_execz .Lgb_join
	s_and_b32 s8, s2, 7
	s_lshl_b32 s8, s8, 3
	s_bfe_u32 s9, s2, 0x30003
	s_add_i32 s8, s8, s9
	s_lshl_b32 s8, s8, 5
	s_add_i32 s8, s8, 0x3600
	s_add_u32 s10, s46, s8
	s_addc_u32 s11, s47, 0
	s_mul_i32 s9, s33, 3
	s_add_i32 s9, s9, 8
	s_lshl_b32 s12, 1, s9
	s_add_i32 s12, s12, 1
	v_mov_b32_e32 v0, 0
	v_mov_b32_e32 v1, s12
	global_atomic_add v0, v1, s[10:11]
	s_mov_b32 s13, 0
.Lgb_poll:
	global_load_dword v2, v0, s[10:11] sc1
	s_waitcnt vmcnt(0)
	v_readfirstlane_b32 s14, v2
	s_and_b32 s15, s14, 0xff
	s_cmp_ge_u32 s15, 4
	s_cbranch_scc1 .Lgb_all
	s_add_i32 s13, s13, 1
	s_cmp_lt_u32 s13, 0x4000
	s_cbranch_scc0 .Lgb_acq
	s_sleep 1
	s_branch .Lgb_poll
.Lgb_all:
	s_lshr_b32 s15, s14, s9
	s_and_b32 s15, s15, 7
	s_cmp_eq_u32 s15, 4
	s_cbranch_scc1 .Lgb_acq
	buffer_wbl2 sc1
	s_waitcnt vmcnt(0)
	v_mov_b32_e32 v1, 1
	global_atomic_add v0, v1, s[10:11] offset:16
	s_mov_b32 s13, 0
.Lgb_poll2:
	global_load_dword v2, v0, s[10:11] offset:16 sc1
	s_waitcnt vmcnt(0)
	v_readfirstlane_b32 s14, v2
	s_cmp_ge_u32 s14, 4
	s_cbranch_scc1 .Lgb_acq
	s_add_i32 s13, s13, 1
	s_cmp_lt_u32 s13, 0x4000
	s_cbranch_scc0 .Lgb_acq
	s_sleep 1
	s_branch .Lgb_poll2
.Lgb_acq:
	buffer_inv sc1
	s_waitcnt vmcnt(0)
.Lgb_join:
	s_or_b64 exec, exec, s[6:7]
	s_waitcnt lgkmcnt(0)
	s_barrier
	s_and_b64 vcc, exec, s[4:5]
	v_readfirstlane_b32 s12, v203
	s_cbranch_vccnz .LBB0_1391
	s_ashr_i32 s6, s2, 31
	s_load_dwordx2 s[4:5], s[0:1], 0xc8
	s_lshr_b32 s6, s6, 29
	s_add_i32 s10, s2, s6
	s_and_b32 s6, s10, -8
	s_sub_i32 s9, s2, s6
	s_cmp_gt_i32 s9, -1
	s_cbranch_scc0 .LBB0_1362
	s_lshl_b32 s8, s9, 5
	s_ashr_i32 s6, s10, 3
	s_cbranch_execz .LBB0_1363
	s_branch .LBB0_1364
